# v26 + per-unit accumulator re-zeroing in the four GEMM bodies uses 64 v_mov_b64 instead of 128 v_mov_b32
# speedup vs baseline: 1.0003x; 1.0003x over previous
; DI const char* a_of(const Gemm& g, const Unit& u) { return (const char*)(g.A + (size_t)u.pz * g.zA + (size_t)u.pm * BM * g.lda); }
; DI const char* b_of(const Gemm& g, const Unit& u) { return (const char*)(g.Bt + (size_t)u.pz * g.zB + (size_t)u.pn * BM * g.ldb); }
; template <class Epi>
; DI void gemm_phase(LAS unsigned char* lds, int tid, const Gemm g, const Order& S, const Epi& E) {
;     ...
;         const bool has_next = S.next(ui + 1, nxt);
;         const char* nA = has_next ? a_of(g, nxt) : cA; const char* nB = has_next ? b_of(g, nxt) : cB;
;     ...
; #pragma unroll
;         for (int a = 0; a < 2; ++a)
; #pragma unroll
;             for (int b = 0; b < 2; ++b)
; #pragma unroll
;                 for (int m = 0; m < 4; ++m)
; #pragma unroll
;                     for (int n = 0; n < 2; ++n) acc[a][b][m][n] = (f32x4){0.f, 0.f, 0.f, 0.f};
;         cur = nxt; cA = nA; cB = nB; ++ui;
.LBB0_386:
	s_ashr_i32 s77, s76, 31
	s_lshl_b64 s[52:53], s[76:77], 19
	s_add_u32 s84, s28, s52
	s_addc_u32 s85, s36, s53
	s_and_b64 s[52:53], s[6:7], exec
	s_cselect_b32 s20, s85, s9
	s_cselect_b32 s33, s84, s8
	s_ashr_i32 s79, s78, 31
	s_lshl_b64 s[52:53], s[78:79], 19
	s_add_u32 s86, s51, s52
	s_addc_u32 s87, s31, s53
	s_and_b64 s[52:53], s[6:7], exec
	s_cselect_b32 s52, s87, s89
	s_cselect_b32 s53, s86, s88
	s_add_u32 s8, s8, 0x40080
	s_addc_u32 s9, s9, 0
	s_add_u32 s77, s88, 0x100
	v_mov_b32_e32 v2, 0
	s_addc_u32 s79, s89, 0
	s_mov_b32 s81, -2
	v_mov_b32_e32 v3, v2
	v_mov_b64_e32 v[4:5], v[2:3]
	v_mov_b64_e32 v[6:7], v[2:3]
	v_mov_b64_e32 v[8:9], v[2:3]
	v_mov_b64_e32 v[10:11], v[2:3]
	v_mov_b64_e32 v[12:13], v[2:3]
	v_mov_b64_e32 v[14:15], v[2:3]
	v_mov_b64_e32 v[16:17], v[2:3]
	v_mov_b64_e32 v[18:19], v[2:3]
	v_mov_b64_e32 v[20:21], v[2:3]
	v_mov_b64_e32 v[22:23], v[2:3]
	v_mov_b64_e32 v[24:25], v[2:3]
	v_mov_b64_e32 v[26:27], v[2:3]
	v_mov_b64_e32 v[28:29], v[2:3]
	v_mov_b64_e32 v[30:31], v[2:3]
	v_mov_b64_e32 v[32:33], v[2:3]
	v_mov_b64_e32 v[34:35], v[2:3]
	v_mov_b64_e32 v[36:37], v[2:3]
	v_mov_b64_e32 v[38:39], v[2:3]
	v_mov_b64_e32 v[40:41], v[2:3]
	v_mov_b64_e32 v[42:43], v[2:3]
	v_mov_b64_e32 v[44:45], v[2:3]
	v_mov_b64_e32 v[46:47], v[2:3]
	v_mov_b64_e32 v[48:49], v[2:3]
	v_mov_b64_e32 v[50:51], v[2:3]
	v_mov_b64_e32 v[52:53], v[2:3]
	v_mov_b64_e32 v[54:55], v[2:3]
	v_mov_b64_e32 v[56:57], v[2:3]
	v_mov_b64_e32 v[58:59], v[2:3]
	v_mov_b64_e32 v[60:61], v[2:3]
	v_mov_b64_e32 v[62:63], v[2:3]
	v_mov_b64_e32 v[64:65], v[2:3]
	v_mov_b64_e32 v[66:67], v[2:3]
	v_mov_b64_e32 v[68:69], v[2:3]
	v_mov_b64_e32 v[70:71], v[2:3]
	v_mov_b64_e32 v[72:73], v[2:3]
	v_mov_b64_e32 v[74:75], v[2:3]
	v_mov_b64_e32 v[76:77], v[2:3]
	v_mov_b64_e32 v[78:79], v[2:3]
	v_mov_b64_e32 v[80:81], v[2:3]
	v_mov_b64_e32 v[82:83], v[2:3]
	v_mov_b64_e32 v[84:85], v[2:3]
	v_mov_b64_e32 v[86:87], v[2:3]
	v_mov_b64_e32 v[88:89], v[2:3]
	v_mov_b64_e32 v[90:91], v[2:3]
	v_mov_b64_e32 v[92:93], v[2:3]
	v_mov_b64_e32 v[94:95], v[2:3]
	v_mov_b64_e32 v[96:97], v[2:3]
	v_mov_b64_e32 v[98:99], v[2:3]
	v_mov_b64_e32 v[100:101], v[2:3]
	v_mov_b64_e32 v[102:103], v[2:3]
	v_mov_b64_e32 v[104:105], v[2:3]
	v_mov_b64_e32 v[106:107], v[2:3]
	v_mov_b64_e32 v[108:109], v[2:3]
	v_mov_b64_e32 v[110:111], v[2:3]
	v_mov_b64_e32 v[112:113], v[2:3]
	v_mov_b64_e32 v[114:115], v[2:3]
	v_mov_b64_e32 v[116:117], v[2:3]
	v_mov_b64_e32 v[118:119], v[2:3]
	v_mov_b64_e32 v[120:121], v[2:3]
	v_mov_b64_e32 v[122:123], v[2:3]
	v_mov_b64_e32 v[124:125], v[2:3]
	v_mov_b64_e32 v[126:127], v[2:3]
	v_mov_b64_e32 v[128:129], v[2:3]

; template <class Epi>
; DI void gemm_phase(LAS unsigned char* lds, int tid, const Gemm g, const Order& S, const Epi& E) {
;     ...
; #pragma unroll
;         for (int a = 0; a < 2; ++a)
; #pragma unroll
;             for (int b = 0; b < 2; ++b)
; #pragma unroll
;                 for (int m = 0; m < 4; ++m)
; #pragma unroll
;                     for (int n = 0; n < 2; ++n) acc[a][b][m][n] = (f32x4){0.f, 0.f, 0.f, 0.f};
;         cur = nxt; cA = nA; cB = nB; ++ui;
.LBB0_465:
	s_add_u32 s90, s90, 0x80
	s_addc_u32 s91, s91, 0
	s_add_u32 s53, s92, 0x100
	v_mov_b32_e32 v2, 0
	s_addc_u32 vcc_lo, s93, 0
	s_mov_b32 s92, 0
	v_mov_b32_e32 v3, v2
	v_mov_b64_e32 v[4:5], v[2:3]
	v_mov_b64_e32 v[6:7], v[2:3]
	v_mov_b64_e32 v[8:9], v[2:3]
	v_mov_b64_e32 v[10:11], v[2:3]
	v_mov_b64_e32 v[12:13], v[2:3]
	v_mov_b64_e32 v[14:15], v[2:3]
	v_mov_b64_e32 v[16:17], v[2:3]
	v_mov_b64_e32 v[18:19], v[2:3]
	v_mov_b64_e32 v[20:21], v[2:3]
	v_mov_b64_e32 v[22:23], v[2:3]
	v_mov_b64_e32 v[24:25], v[2:3]
	v_mov_b64_e32 v[26:27], v[2:3]
	v_mov_b64_e32 v[28:29], v[2:3]
	v_mov_b64_e32 v[30:31], v[2:3]
	v_mov_b64_e32 v[32:33], v[2:3]
	v_mov_b64_e32 v[34:35], v[2:3]
	v_mov_b64_e32 v[36:37], v[2:3]
	v_mov_b64_e32 v[38:39], v[2:3]
	v_mov_b64_e32 v[40:41], v[2:3]
	v_mov_b64_e32 v[42:43], v[2:3]
	v_mov_b64_e32 v[44:45], v[2:3]
	v_mov_b64_e32 v[46:47], v[2:3]
	v_mov_b64_e32 v[48:49], v[2:3]
	v_mov_b64_e32 v[50:51], v[2:3]
	v_mov_b64_e32 v[52:53], v[2:3]
	v_mov_b64_e32 v[54:55], v[2:3]
	v_mov_b64_e32 v[56:57], v[2:3]
	v_mov_b64_e32 v[58:59], v[2:3]
	v_mov_b64_e32 v[60:61], v[2:3]
	v_mov_b64_e32 v[62:63], v[2:3]
	v_mov_b64_e32 v[64:65], v[2:3]
	v_mov_b64_e32 v[66:67], v[2:3]
	v_mov_b64_e32 v[68:69], v[2:3]
	v_mov_b64_e32 v[70:71], v[2:3]
	v_mov_b64_e32 v[72:73], v[2:3]
	v_mov_b64_e32 v[74:75], v[2:3]
	v_mov_b64_e32 v[76:77], v[2:3]
	v_mov_b64_e32 v[78:79], v[2:3]
	v_mov_b64_e32 v[80:81], v[2:3]
	v_mov_b64_e32 v[82:83], v[2:3]
	v_mov_b64_e32 v[84:85], v[2:3]
	v_mov_b64_e32 v[86:87], v[2:3]
	v_mov_b64_e32 v[88:89], v[2:3]
	v_mov_b64_e32 v[90:91], v[2:3]
	v_mov_b64_e32 v[92:93], v[2:3]
	v_mov_b64_e32 v[94:95], v[2:3]
	v_mov_b64_e32 v[96:97], v[2:3]
	v_mov_b64_e32 v[98:99], v[2:3]
	v_mov_b64_e32 v[100:101], v[2:3]
	v_mov_b64_e32 v[102:103], v[2:3]
	v_mov_b64_e32 v[104:105], v[2:3]
	v_mov_b64_e32 v[106:107], v[2:3]
	v_mov_b64_e32 v[108:109], v[2:3]
	v_mov_b64_e32 v[110:111], v[2:3]
	v_mov_b64_e32 v[112:113], v[2:3]
	v_mov_b64_e32 v[114:115], v[2:3]
	v_mov_b64_e32 v[116:117], v[2:3]
	v_mov_b64_e32 v[118:119], v[2:3]
	v_mov_b64_e32 v[120:121], v[2:3]
	v_mov_b64_e32 v[122:123], v[2:3]
	v_mov_b64_e32 v[124:125], v[2:3]
	v_mov_b64_e32 v[126:127], v[2:3]
	v_mov_b64_e32 v[128:129], v[2:3]

; template <class Epi>
; DI void gemm_phase(LAS unsigned char* lds, int tid, const Gemm g, const Order& S, const Epi& E) {
;     ...
; #pragma unroll
;         for (int a = 0; a < 2; ++a)
; #pragma unroll
;             for (int b = 0; b < 2; ++b)
; #pragma unroll
;                 for (int m = 0; m < 4; ++m)
; #pragma unroll
;                     for (int n = 0; n < 2; ++n) acc[a][b][m][n] = (f32x4){0.f, 0.f, 0.f, 0.f};
;         cur = nxt; cA = nA; cB = nB; ++ui;
.LBB0_492:
	s_add_u32 s84, s84, 0x80
	s_addc_u32 s85, s85, 0
	s_add_u32 s30, s86, 0x100
	v_mov_b32_e32 v2, 0
	s_addc_u32 s31, s87, 0
	s_mov_b32 s33, 0
	v_mov_b32_e32 v3, v2
	v_mov_b64_e32 v[4:5], v[2:3]
	v_mov_b64_e32 v[6:7], v[2:3]
	v_mov_b64_e32 v[8:9], v[2:3]
	v_mov_b64_e32 v[10:11], v[2:3]
	v_mov_b64_e32 v[12:13], v[2:3]
	v_mov_b64_e32 v[14:15], v[2:3]
	v_mov_b64_e32 v[16:17], v[2:3]
	v_mov_b64_e32 v[18:19], v[2:3]
	v_mov_b64_e32 v[20:21], v[2:3]
	v_mov_b64_e32 v[22:23], v[2:3]
	v_mov_b64_e32 v[24:25], v[2:3]
	v_mov_b64_e32 v[26:27], v[2:3]
	v_mov_b64_e32 v[28:29], v[2:3]
	v_mov_b64_e32 v[30:31], v[2:3]
	v_mov_b64_e32 v[32:33], v[2:3]
	v_mov_b64_e32 v[34:35], v[2:3]
	v_mov_b64_e32 v[36:37], v[2:3]
	v_mov_b64_e32 v[38:39], v[2:3]
	v_mov_b64_e32 v[40:41], v[2:3]
	v_mov_b64_e32 v[42:43], v[2:3]
	v_mov_b64_e32 v[44:45], v[2:3]
	v_mov_b64_e32 v[46:47], v[2:3]
	v_mov_b64_e32 v[48:49], v[2:3]
	v_mov_b64_e32 v[50:51], v[2:3]
	v_mov_b64_e32 v[52:53], v[2:3]
	v_mov_b64_e32 v[54:55], v[2:3]
	v_mov_b64_e32 v[56:57], v[2:3]
	v_mov_b64_e32 v[58:59], v[2:3]
	v_mov_b64_e32 v[60:61], v[2:3]
	v_mov_b64_e32 v[62:63], v[2:3]
	v_mov_b64_e32 v[64:65], v[2:3]
	v_mov_b64_e32 v[66:67], v[2:3]
	v_mov_b64_e32 v[68:69], v[2:3]
	v_mov_b64_e32 v[70:71], v[2:3]
	v_mov_b64_e32 v[72:73], v[2:3]
	v_mov_b64_e32 v[74:75], v[2:3]
	v_mov_b64_e32 v[76:77], v[2:3]
	v_mov_b64_e32 v[78:79], v[2:3]
	v_mov_b64_e32 v[80:81], v[2:3]
	v_mov_b64_e32 v[82:83], v[2:3]
	v_mov_b64_e32 v[84:85], v[2:3]
	v_mov_b64_e32 v[86:87], v[2:3]
	v_mov_b64_e32 v[88:89], v[2:3]
	v_mov_b64_e32 v[90:91], v[2:3]
	v_mov_b64_e32 v[92:93], v[2:3]
	v_mov_b64_e32 v[94:95], v[2:3]
	v_mov_b64_e32 v[96:97], v[2:3]
	v_mov_b64_e32 v[98:99], v[2:3]
	v_mov_b64_e32 v[100:101], v[2:3]
	v_mov_b64_e32 v[102:103], v[2:3]
	v_mov_b64_e32 v[104:105], v[2:3]
	v_mov_b64_e32 v[106:107], v[2:3]
	v_mov_b64_e32 v[108:109], v[2:3]
	v_mov_b64_e32 v[110:111], v[2:3]
	v_mov_b64_e32 v[112:113], v[2:3]
	v_mov_b64_e32 v[114:115], v[2:3]
	v_mov_b64_e32 v[116:117], v[2:3]
	v_mov_b64_e32 v[118:119], v[2:3]
	v_mov_b64_e32 v[120:121], v[2:3]
	v_mov_b64_e32 v[122:123], v[2:3]
	v_mov_b64_e32 v[124:125], v[2:3]
	v_mov_b64_e32 v[126:127], v[2:3]
	v_mov_b64_e32 v[128:129], v[2:3]

; DI const char* a_of(const Gemm& g, const Unit& u) { return (const char*)(g.A + (size_t)u.pz * g.zA + (size_t)u.pm * BM * g.lda); }
; DI const char* b_of(const Gemm& g, const Unit& u) { return (const char*)(g.Bt + (size_t)u.pz * g.zB + (size_t)u.pn * BM * g.ldb); }
; template <class Epi>
; DI void gemm_phase(LAS unsigned char* lds, int tid, const Gemm g, const Order& S, const Epi& E) {
;     ...
;         const bool has_next = S.next(ui + 1, nxt);
;         const char* nA = has_next ? a_of(g, nxt) : cA; const char* nB = has_next ? b_of(g, nxt) : cB;
;     ...
; #pragma unroll
;         for (int a = 0; a < 2; ++a)
; #pragma unroll
;             for (int b = 0; b < 2; ++b)
; #pragma unroll
;                 for (int m = 0; m < 4; ++m)
; #pragma unroll
;                     for (int n = 0; n < 2; ++n) acc[a][b][m][n] = (f32x4){0.f, 0.f, 0.f, 0.f};
;         cur = nxt; cA = nA; cB = nB; ++ui;
.LBB0_512:
	s_ashr_i32 s67, s66, 31
	s_lshl_b64 s[40:41], s[66:67], 19
	s_add_u32 s68, s58, s40
	s_addc_u32 s69, s59, s41
	s_and_b64 s[40:41], s[4:5], exec
	s_cselect_b32 s39, s69, s75
	s_cselect_b32 s40, s68, s74
	s_ashr_i32 s65, s64, 31
	s_lshl_b64 s[46:47], s[64:65], 19
	s_add_u32 s70, s10, s46
	s_addc_u32 s71, s11, s47
	s_and_b64 s[46:47], s[4:5], exec
	s_cselect_b32 s41, s71, s77
	s_cselect_b32 s43, s70, s76
	s_add_u32 s74, s74, 0x40080
	s_addc_u32 s75, s75, 0
	s_add_u32 s45, s76, 0x100
	v_mov_b32_e32 v2, 0
	s_addc_u32 s46, s77, 0
	s_mov_b32 s47, -2
	v_mov_b32_e32 v3, v2
	v_mov_b64_e32 v[4:5], v[2:3]
	v_mov_b64_e32 v[6:7], v[2:3]
	v_mov_b64_e32 v[8:9], v[2:3]
	v_mov_b64_e32 v[10:11], v[2:3]
	v_mov_b64_e32 v[12:13], v[2:3]
	v_mov_b64_e32 v[14:15], v[2:3]
	v_mov_b64_e32 v[16:17], v[2:3]
	v_mov_b64_e32 v[18:19], v[2:3]
	v_mov_b64_e32 v[20:21], v[2:3]
	v_mov_b64_e32 v[22:23], v[2:3]
	v_mov_b64_e32 v[24:25], v[2:3]
	v_mov_b64_e32 v[26:27], v[2:3]
	v_mov_b64_e32 v[28:29], v[2:3]
	v_mov_b64_e32 v[30:31], v[2:3]
	v_mov_b64_e32 v[32:33], v[2:3]
	v_mov_b64_e32 v[34:35], v[2:3]
	v_mov_b64_e32 v[36:37], v[2:3]
	v_mov_b64_e32 v[38:39], v[2:3]
	v_mov_b64_e32 v[40:41], v[2:3]
	v_mov_b64_e32 v[42:43], v[2:3]
	v_mov_b64_e32 v[44:45], v[2:3]
	v_mov_b64_e32 v[46:47], v[2:3]
	v_mov_b64_e32 v[48:49], v[2:3]
	v_mov_b64_e32 v[50:51], v[2:3]
	v_mov_b64_e32 v[52:53], v[2:3]
	v_mov_b64_e32 v[54:55], v[2:3]
	v_mov_b64_e32 v[56:57], v[2:3]
	v_mov_b64_e32 v[58:59], v[2:3]
	v_mov_b64_e32 v[60:61], v[2:3]
	v_mov_b64_e32 v[62:63], v[2:3]
	v_mov_b64_e32 v[64:65], v[2:3]
	v_mov_b64_e32 v[66:67], v[2:3]
	v_mov_b64_e32 v[68:69], v[2:3]
	v_mov_b64_e32 v[70:71], v[2:3]
	v_mov_b64_e32 v[72:73], v[2:3]
	v_mov_b64_e32 v[74:75], v[2:3]
	v_mov_b64_e32 v[76:77], v[2:3]
	v_mov_b64_e32 v[78:79], v[2:3]
	v_mov_b64_e32 v[80:81], v[2:3]
	v_mov_b64_e32 v[82:83], v[2:3]
	v_mov_b64_e32 v[84:85], v[2:3]
	v_mov_b64_e32 v[86:87], v[2:3]
	v_mov_b64_e32 v[88:89], v[2:3]
	v_mov_b64_e32 v[90:91], v[2:3]
	v_mov_b64_e32 v[92:93], v[2:3]
	v_mov_b64_e32 v[94:95], v[2:3]
	v_mov_b64_e32 v[96:97], v[2:3]
	v_mov_b64_e32 v[98:99], v[2:3]
	v_mov_b64_e32 v[100:101], v[2:3]
	v_mov_b64_e32 v[102:103], v[2:3]
	v_mov_b64_e32 v[104:105], v[2:3]
	v_mov_b64_e32 v[106:107], v[2:3]
	v_mov_b64_e32 v[108:109], v[2:3]
	v_mov_b64_e32 v[110:111], v[2:3]
	v_mov_b64_e32 v[112:113], v[2:3]
	v_mov_b64_e32 v[114:115], v[2:3]
	v_mov_b64_e32 v[116:117], v[2:3]
	v_mov_b64_e32 v[118:119], v[2:3]
	v_mov_b64_e32 v[120:121], v[2:3]
	v_mov_b64_e32 v[122:123], v[2:3]
	v_mov_b64_e32 v[124:125], v[2:3]
	v_mov_b64_e32 v[126:127], v[2:3]
	v_mov_b64_e32 v[128:129], v[2:3]
